# G3 pairing: one queue pop handles GLA-output units (c,h) and (c,h+1) with shared latency chain (loads of both issued together, one mid barrier), on top of v78
# speedup vs baseline: 1.0016x; 1.0008x over previous
; #define WSB(off) (wsp(F) + (off))
; __global__ void __launch_bounds__(NWAVES * 64, 2) hymba_fwd(Args args) {
;     ...
;         for (int it = 0;; ++it) {
;             if (it == 0) __syncthreads();
;             volatile LAS int* slot = (volatile LAS int*)(F.lds + MISC_OFF) + 16 + (it & 1);
;             if (threadIdx.x == 0) *slot = (int)__hip_atomic_fetch_add((unsigned*)(CTL_ + CW_QUEUE + 64 * (l + 4 * rep)), 1u, __ATOMIC_RELAXED, __HIP_MEMORY_SCOPE_AGENT);
;             __syncthreads();
;             const int idx = __builtin_amdgcn_readfirstlane(*slot);
;             if (idx >= 128 + 512 + NCHUNK * 4) break;
;             if (idx < 64) { const int cS = NPCH + (idx >> 2), hS = idx & 3; G1IN_DECL(gS);
;                 gla::g1_load(G1IN_ARGS(gS), cS, hS, ACT_, LOGA_, inp(F, 7) + (size_t)l * 256);
;                 gla::g1_unit<false>(F.lds + RING_OFF, G1IN_ARGS(gS), cS, hS, l, (bf16*)WSB(WS_U), (float*)WSB(WS_D), (bf16*)WSB(WS_OI), (bf16*)WSB(WS_QT), (bf16*)WSB(WS_SC),
;                              inp(F, 4) + (size_t)l * DECB * 4 * 8192, outp(F) + OG_S + (size_t)l * DECB * 4 * 8192, G1IN_ARGS(gS), cS, hS, ACT_, LOGA_, inp(F, 7) + (size_t)l * 256);
;                 CNT_SIGNAL(CTL_ + CW_QUEUE + 64 * l + 32, 1);
;             } else if (idx < 128) { const int b = (idx - 64) >> 2, h = idx & 3;
;                 const float* kc = inp(F, 2) + ((size_t)(l * DECB + b) * PAST) * 512 + h * 128; const float* vc = inp(F, 3) + ((size_t)(l * DECB + b) * PAST) * 512 + h * 128;
;                 const float* kn = outp(F) + OK_S + ((size_t)(l * DECB + b) * 64) * 512 + h * 128; const float* vn = outp(F) + OV_S + ((size_t)(l * DECB + b) * 64) * 512 + h * 128;
;     ...
;                 att::attn_unit_sample(F.lds + RING_OFF, kc, vc, kn, vn, ACT_ + (size_t)(SEQ + 64 * b) * NIN + 1792 + h * 128, MIX_ + (size_t)(SEQ + 64 * b) * DM + 512 + h * 128,
;                                       PAST, h, inp(F, 10) + (size_t)l * 128);
;     ...
;             } else if (idx < 640) { const int i = idx - 128, u = 127 - (i >> 2), h = i & 3;
;     ...
;                 int i2 = i; asm volatile("" : "+s"(i2));
;                 if (att::attn_unit_prompt_t<false>(F.lds + RING_OFF, ACT_ + 2304 + h * 128, ACT_ + 2816 + h * 128, ACT_ + (size_t)(128 * u) * NIN + 1792 + h * 128,
;                                       MIX_ + (size_t)(128 * u) * DM + 512 + h * 128, 2 * u + 2, 128 * u, h, inp(F, 10) + (size_t)l * 128)) {
.LBB0_474:
	s_or_b64 exec, exec, s[0:1]
	v_mov_b32_e32 v3, s10
	s_waitcnt lgkmcnt(0)
	s_barrier
	ds_read_b32 v3, v3
	s_xor_b64 s[8:9], s[96:97], -1
	s_xor_b64 s[12:13], s[84:85], -1
	s_waitcnt lgkmcnt(0)
	v_readfirstlane_b32 s53, v3
	s_cmpk_gt_i32 s53, 0x49f
	s_cselect_b64 s[44:45], -1, 0
	s_and_b64 vcc, exec, s[44:45]
	s_cbranch_vccnz .LBB0_467
	s_cmp_gt_i32 s53, 63
	s_mov_b64 s[10:11], -1
	s_cbranch_scc0 .LBB0_686
	s_cmpk_gt_u32 s53, 0x7f
	s_cbranch_scc0 .LBB0_631
	s_cmpk_gt_u32 s53, 0x27f
	s_cbranch_scc0 .LBB0_520
	s_add_i32 s20, s53, 0xfffffd80
	s_lshl_b32 s20, s20, 1
	s_mov_b64 s[0:1], -1
	s_mov_b64 s[10:11], 0
	s_cmpk_gt_u32 s20, 0x3ff
	s_mov_b64 s[6:7], -1
	s_cbranch_scc0 .LBB0_496
	s_mov_b64 s[6:7], 0
	s_and_b64 vcc, exec, s[12:13]
	s_cbranch_vccz .LBB0_496
	s_and_saveexec_b64 s[10:11], s[38:39]
	s_cbranch_execz .LBB0_495
	v_mov_b32_e32 v3, 0x20258
	s_mov_b32 s21, 1
	v_add_u32_e32 v3, 0, v3
	ds_read_b32 v4, v3
	ds_read_b32 v3, v3 offset:4
	s_waitcnt lgkmcnt(1)
	v_readfirstlane_b32 s12, v4
	s_waitcnt lgkmcnt(0)
	v_readfirstlane_b32 s13, v3
	s_add_u32 s12, s12, 0x4200
	s_addc_u32 s13, s13, 0
	s_branch .LBB0_483

; #define LAS __attribute__((address_space(3)))
; __device__ __forceinline__ int fresh_tid() { int t = threadIdx.x; asm volatile("" : "+v"(t)); return t; }
; __device__ __forceinline__ void g3_unit(LAS float* part, int c, int h, const bf16* ACT, const bf16* OI, const bf16* QT, const bf16* SCT, const float* gnorm  , bf16* MIX) {
;     const int tid = fresh_tid(), wid = __builtin_amdgcn_readfirstlane(tid >> 6), lane = tid & 63, r = lane & 31, hh = lane >> 5;
;     const int jb = wid >> 1, tb = wid & 1; const int row = 64 * c + tb * 32 + r;
;     f32x16 acc = {};
;     const bf16* ap = SCT + ((size_t)(c * 4 + h) * 128 + jb * 32 + r) * 64 + 8 * hh; const bf16* bp = QT + (size_t)row * 256 + h * 64 + 8 * hh;
; #pragma unroll
;     for (int kk = 0; kk < 4; ++kk) acc = __builtin_amdgcn_mfma_f32_32x32x16_bf16(*(const bf16x8*)(ap + kk * 16), *(const bf16x8*)(bp + kk * 16), acc, 0, 0, 0);
;     const int j0 = jb * 32 + 4 * hh;
;     const bf16* oip = OI + (size_t)row * 512 + h * 128 + j0;
;     const bf16* gp = ACT + (size_t)row * NIN + 1280 + h * 128 + j0;
;     v2u ggv[4]; f32x4 gnv[4];
; #pragma unroll
;     for (int q = 0; q < 4; ++q) { ggv[q] = *(const v2u*)(gp + 8 * q); gnv[q] = *(const f32x4*)(gnorm + j0 + 8 * q); }
.Lpf_skip_g3:
	s_or_b64 exec, exec, s[8:9]
	v_mov_b32_e32 v3, 0x20258
	v_mov_b32_e32 v6, 0x20200
	v_add_u32_e32 v3, 0, v3
	s_waitcnt vmcnt(4)
	ds_read_b32 v32, v3
	ds_read_b32 v33, v3 offset:4
	v_mov_b32_e32 v3, 0x20258
	s_lshr_b32 s8, s20, 2
	v_add_u32_e32 v3, 0, v3
	ds_read_b32 v16, v3
	ds_read_b32 v17, v3 offset:4
	v_mov_b32_e32 v3, 0x20258
	s_and_b32 s18, s20, 3
	v_add_u32_e32 v3, 0, v3
	ds_read_b32 v4, v3
	ds_read_b32 v3, v3 offset:4
	v_readlane_b32 s14, v255, 0
	v_readlane_b32 s15, v255, 1
	s_waitcnt lgkmcnt(1)
	v_readfirstlane_b32 s12, v4
	v_mov_b32_e32 v4, 0x20258
	s_waitcnt lgkmcnt(0)
	v_readfirstlane_b32 s13, v3
	v_add_u32_e32 v4, 0, v4
	ds_read_b32 v5, v4
	ds_read_b32 v4, v4 offset:4
	v_mov_b32_e32 v3, 0x20258
	v_add_u32_e32 v6, 0, v6
	ds_read_b32 v7, v6
	ds_read_b32 v6, v6 offset:4
	s_waitcnt lgkmcnt(2)
	v_readfirstlane_b32 s17, v4
	v_add_u32_e32 v3, 0, v3
	s_waitcnt lgkmcnt(1)
	v_readfirstlane_b32 s9, v7
	v_mov_b32_e32 v4, v0
	s_waitcnt lgkmcnt(0)
	v_readfirstlane_b32 s11, v6
	s_add_u32 s10, s9, s14
	ds_read_b32 v53, v3
	ds_read_b32 v74, v3 offset:4
	s_addc_u32 s11, s11, s15
	v_readfirstlane_b32 s9, v4
	s_ashr_i32 s15, s9, 6
	s_lshl_b32 s14, s15, 5
	s_lshl_b32 s19, s8, 6
	s_and_b32 s14, s14, 32
	v_and_b32_e32 v3, 31, v4
	s_or_b32 s19, s14, s19
	s_lshl_b32 s8, s8, 9
	s_lshl_b32 s72, s18, 7
	v_or_b32_e32 v196, s19, v3
	s_or_b32 s19, s8, s72
	s_ashr_i32 s8, s9, 2
	s_andn2_b32 s8, s8, 31
	s_ashr_i32 s9, s8, 31
	s_add_u32 s19, s8, s19
	s_addc_u32 s20, s9, 0
	v_readfirstlane_b32 s16, v5
	v_bfe_u32 v52, v4, 5, 1
	v_or_b32_e32 v4, s19, v3
	v_mov_b32_e32 v5, s20
	v_lshlrev_b64 v[4:5], 7, v[4:5]
	v_lshl_add_u64 v[4:5], s[16:17], 0, v[4:5]
	v_lshlrev_b32_e32 v6, 4, v52
	v_mov_b32_e32 v7, v197
	v_lshl_add_u64 v[12:13], v[4:5], 0, v[6:7]
	v_lshlrev_b64 v[4:5], 9, v[196:197]
	v_lshl_add_u64 v[4:5], s[12:13], 0, v[4:5]
	v_lshl_add_u64 v[4:5], v[4:5], 0, s[72:73]
	s_mov_b32 s12, 0x1f100000
	v_lshl_add_u64 v[14:15], v[4:5], 0, v[6:7]
	v_add_co_u32_e32 v4, vcc, s12, v12
	s_mov_b32 s12, 0x23300000
	s_nop 0
	v_addc_co_u32_e32 v5, vcc, 0, v13, vcc
	global_load_dwordx4 v[4:7], v[4:5], off
	v_add_co_u32_e32 v8, vcc, s12, v14
	s_mov_b64 s[12:13], 0x1f100000
	s_nop 0
	v_addc_co_u32_e32 v9, vcc, 0, v15, vcc
	global_load_dwordx4 v[8:11], v[8:9], off
	v_lshl_add_u64 v[12:13], v[12:13], 0, s[12:13]
	s_mov_b64 s[26:27], 0x4000
	v_lshl_add_u64 v[150:151], v[12:13], 0, s[26:27]
	global_load_dwordx4 v[20:23], v[12:13], off offset:32
	s_mov_b64 s[16:17], 0x23300000
	v_lshl_add_u64 v[14:15], v[14:15], 0, s[16:17]
	global_load_dwordx4 v[24:27], v[14:15], off offset:32
	global_load_dwordx4 v[54:57], v[12:13], off offset:64
	global_load_dwordx4 v[58:61], v[14:15], off offset:64
	v_readfirstlane_b32 s12, v16
	v_readfirstlane_b32 s13, v17
	v_lshl_or_b32 v16, v52, 2, s8
	v_lshlrev_b64 v[18:19], 10, v[196:197]
	v_ashrrev_i32_e32 v17, 31, v16
	s_lshl_b32 s16, s18, 8
	s_mov_b32 s17, s73
	v_lshl_add_u64 v[18:19], s[12:13], 0, v[18:19]
	s_waitcnt vmcnt(9)
	v_lshlrev_b64 v[28:29], 1, v[16:17]
	v_lshl_add_u64 v[18:19], v[18:19], 0, s[16:17]
	v_lshl_add_u64 v[18:19], v[18:19], 0, v[28:29]
	s_mov_b32 s12, 0x21100000
	v_add_co_u32_e32 v30, vcc, s12, v18
	s_mov_b64 s[12:13], 0x21100000
	s_nop 0
	v_addc_co_u32_e32 v31, vcc, 0, v19, vcc
	global_load_dwordx2 v[38:39], v[30:31], off
	global_load_dwordx4 v[62:65], v[12:13], off offset:96
	v_lshl_add_u64 v[12:13], v[18:19], 0, s[12:13]
	v_lshl_add_u64 v[154:155], v[18:19], 0, s[12:13]
	global_load_dwordx2 v[42:43], v[12:13], off offset:16
	global_load_dwordx4 v[66:69], v[14:15], off offset:96
	global_load_dwordx2 v[70:71], v[12:13], off offset:32
	global_load_dwordx2 v[72:73], v[12:13], off offset:48
	v_readfirstlane_b32 s12, v32
	v_readfirstlane_b32 s13, v33
	v_lshl_add_u64 v[46:47], v[16:17], 2, s[10:11]
	v_mov_b32_e32 v12, s12
	v_mov_b32_e32 v13, s13
	v_mad_u64_u32 v[12:13], s[12:13], v196, s90, v[12:13]
	v_lshl_add_u64 v[12:13], v[12:13], 0, s[16:17]
	v_lshl_add_u64 v[28:29], v[12:13], 0, v[28:29]
	s_mov_b64 s[12:13], 0xce00a00
	s_mov_b32 s10, 0xce00000
	v_lshl_add_u64 v[36:37], v[28:29], 0, s[12:13]
	v_lshl_add_u64 v[152:153], v[28:29], 0, s[12:13]
	v_add_co_u32_e32 v28, vcc, s10, v28
	s_waitcnt lgkmcnt(1)
	v_readfirstlane_b32 s10, v53
	v_addc_co_u32_e32 v29, vcc, 0, v29, vcc
	global_load_dwordx2 v[48:49], v[28:29], off offset:2560
	global_load_dwordx4 v[32:35], v[46:47], off
	s_nop 0
	global_load_dwordx4 v[28:31], v[46:47], off offset:32
	global_load_dwordx2 v[44:45], v[36:37], off offset:16
	global_load_dwordx2 v[40:41], v[36:37], off offset:32
	s_nop 0
	global_load_dwordx2 v[36:37], v[36:37], off offset:48
	s_waitcnt lgkmcnt(0)
	v_readfirstlane_b32 s11, v74
	v_mov_b32_e32 v75, v3
	v_mov_b32_e32 v148, v196
	v_mov_b32_e32 v149, 0
	v_mov_b32_e32 v118, v46
	v_mov_b32_e32 v119, v47
	global_load_dwordx4 v[76:79], v[150:151], off
	global_load_dwordx4 v[80:83], v[14:15], off offset:128
	global_load_dwordx4 v[92:95], v[150:151], off offset:32
	global_load_dwordx4 v[96:99], v[14:15], off offset:160
	global_load_dwordx4 v[126:129], v[150:151], off offset:64
	global_load_dwordx4 v[130:133], v[14:15], off offset:192
	global_load_dwordx2 v[110:111], v[154:155], off offset:256
	global_load_dwordx4 v[134:137], v[150:151], off offset:96
	global_load_dwordx2 v[114:115], v[154:155], off offset:272
	global_load_dwordx4 v[138:141], v[14:15], off offset:224
	global_load_dwordx2 v[142:143], v[154:155], off offset:288
	global_load_dwordx2 v[144:145], v[154:155], off offset:304
	global_load_dwordx2 v[120:121], v[152:153], off offset:256
	global_load_dwordx4 v[104:107], v[46:47], off
	global_load_dwordx4 v[100:103], v[46:47], off offset:32
	global_load_dwordx2 v[116:117], v[152:153], off offset:272
	global_load_dwordx2 v[112:113], v[152:153], off offset:288
	global_load_dwordx2 v[108:109], v[152:153], off offset:304
	s_waitcnt vmcnt(34)
; __device__ __forceinline__ void g3_unit(LAS float* part, int c, int h, const bf16* ACT, const bf16* OI, const bf16* QT, const bf16* SCT, const float* gnorm  , bf16* MIX) {
;     ...
;     float ss = 0.f;
; #pragma unroll
;     for (int q = 0; q < 4; ++q) { const v2u ow = *(const v2u*)(oip + 8 * q);
;       const float oi[4] = {__builtin_bit_cast(float, ow.x << 16), __builtin_bit_cast(float, ow.x & 0xffff0000u), __builtin_bit_cast(float, ow.y << 16), __builtin_bit_cast(float, ow.y & 0xffff0000u)};
; #pragma unroll
;       for (int e = 0; e < 4; ++e) { acc[4 * q + e] += oi[e]; ss += acc[4 * q + e] * acc[4 * q + e]; } }
;     ss += __shfl_xor(ss, 32);
;     if (hh == 0) part[wid * 32 + r] = ss;
	v_mfma_f32_32x32x16_bf16 v[4:19], v[4:7], v[8:11], 0
	s_waitcnt vmcnt(32)
	v_mfma_f32_32x32x16_bf16 v[4:19], v[20:23], v[24:27], v[4:19]
	global_load_dwordx4 v[24:27], v[46:47], off offset:64
	global_load_dwordx4 v[20:23], v[46:47], off offset:96
	s_waitcnt vmcnt(31)
	v_lshlrev_b32_e32 v46, 16, v38
	v_mfma_f32_32x32x16_bf16 v[4:19], v[54:57], v[58:61], v[4:19]
	v_and_b32_e32 v47, 0xffff0000, v38
	v_lshlrev_b32_e32 v38, 16, v39
	v_and_b32_e32 v39, 0xffff0000, v39
	s_waitcnt vmcnt(29)
	v_lshlrev_b32_e32 v54, 16, v42
	v_and_b32_e32 v55, 0xffff0000, v42
	v_lshlrev_b32_e32 v42, 16, v43
	v_and_b32_e32 v43, 0xffff0000, v43
	s_waitcnt vmcnt(28)
	v_mfma_f32_32x32x16_bf16 v[4:19], v[62:65], v[66:69], v[4:19]
	s_nop 11
	v_pk_add_f32 v[50:51], v[4:5], v[46:47]
	v_pk_add_f32 v[4:5], v[6:7], v[38:39]
	v_pk_add_f32 v[46:47], v[8:9], v[54:55]
	v_pk_mul_f32 v[54:55], v[50:51], v[50:51]
	v_pk_mul_f32 v[56:57], v[4:5], v[4:5]
	v_add_f32_e32 v54, v54, v55
	v_add_f32_e32 v54, v56, v54
	v_pk_mul_f32 v[58:59], v[46:47], v[46:47]
	v_add_f32_e32 v54, v57, v54
	v_pk_add_f32 v[6:7], v[10:11], v[42:43]
	v_add_f32_e32 v54, v58, v54
	v_pk_mul_f32 v[60:61], v[6:7], v[6:7]
	s_waitcnt vmcnt(27)
	v_lshlrev_b32_e32 v8, 16, v70
	v_and_b32_e32 v9, 0xffff0000, v70
	v_add_f32_e32 v54, v59, v54
	v_pk_add_f32 v[42:43], v[12:13], v[8:9]
	v_add_f32_e32 v54, v60, v54
	v_pk_mul_f32 v[12:13], v[42:43], v[42:43]
	v_lshlrev_b32_e32 v8, 16, v71
	v_and_b32_e32 v9, 0xffff0000, v71
	v_add_f32_e32 v54, v61, v54
	v_pk_add_f32 v[38:39], v[14:15], v[8:9]
	v_add_f32_e32 v12, v12, v54
	v_pk_mul_f32 v[14:15], v[38:39], v[38:39]
	s_waitcnt vmcnt(26)
	v_lshlrev_b32_e32 v8, 16, v72
	v_and_b32_e32 v9, 0xffff0000, v72
	v_add_f32_e32 v12, v13, v12
	v_pk_add_f32 v[10:11], v[16:17], v[8:9]
	v_add_f32_e32 v12, v14, v12
	v_pk_mul_f32 v[16:17], v[10:11], v[10:11]
	v_lshlrev_b32_e32 v8, 16, v73
	v_and_b32_e32 v9, 0xffff0000, v73
	v_add_f32_e32 v12, v15, v12
	v_and_b32_e32 v14, 64, v239
	v_pk_add_f32 v[8:9], v[18:19], v[8:9]
	v_add_f32_e32 v12, v16, v12
	v_xor_b32_e32 v13, 32, v239
	v_add_u32_e32 v14, 64, v14
	v_pk_mul_f32 v[18:19], v[8:9], v[8:9]
	v_add_f32_e32 v12, v17, v12
	v_cmp_lt_i32_e32 vcc, v13, v14
	v_add_f32_e32 v12, v18, v12
	v_add_f32_e32 v12, v19, v12
	v_cndmask_b32_e32 v13, v239, v13, vcc
	v_lshlrev_b32_e32 v13, 2, v13
	ds_bpermute_b32 v13, v13, v12
	v_cmp_eq_u32_e32 vcc, 0, v52
	s_and_saveexec_b64 s[12:13], vcc
	s_cbranch_execz .LBB0_519
	s_lshl_b32 s15, s15, 7
	s_add_i32 s15, s15, 0
	s_waitcnt lgkmcnt(0)
	v_add_f32_e32 v12, v12, v13
	v_lshl_add_u32 v13, v3, 2, s15
	v_add_u32_e32 v13, 0x1c900, v13
	ds_write_b32 v13, v12
.LBB0_519:
	s_or_b64 exec, exec, s[12:13]
	s_lshl_b32 s12, s14, 2
	s_add_i32 s12, s12, 0
	v_lshl_add_u32 v3, v3, 2, s12
	v_add_u32_e32 v3, 0x1c900, v3
	s_waitcnt vmcnt(18)
	v_mfma_f32_32x32x16_bf16 v[76:91], v[76:79], v[80:83], 0
	s_waitcnt vmcnt(16)
	v_mfma_f32_32x32x16_bf16 v[76:91], v[92:95], v[96:99], v[76:91]
	global_load_dwordx4 v[96:99], v[118:119], off offset:64
	global_load_dwordx4 v[92:95], v[118:119], off offset:96
	s_waitcnt vmcnt(15)
	v_lshlrev_b32_e32 v118, 16, v110
	v_mfma_f32_32x32x16_bf16 v[76:91], v[126:129], v[130:133], v[76:91]
	v_and_b32_e32 v119, 0xffff0000, v110
	v_lshlrev_b32_e32 v110, 16, v111
	v_and_b32_e32 v111, 0xffff0000, v111
	s_waitcnt vmcnt(13)
	v_lshlrev_b32_e32 v126, 16, v114
	v_and_b32_e32 v127, 0xffff0000, v114
	v_lshlrev_b32_e32 v114, 16, v115
	v_and_b32_e32 v115, 0xffff0000, v115
	s_waitcnt vmcnt(12)
	v_mfma_f32_32x32x16_bf16 v[76:91], v[134:137], v[138:141], v[76:91]
	s_nop 11
	v_pk_add_f32 v[122:123], v[76:77], v[118:119]
	v_pk_add_f32 v[76:77], v[78:79], v[110:111]
	v_pk_add_f32 v[118:119], v[80:81], v[126:127]
	v_pk_mul_f32 v[126:127], v[122:123], v[122:123]
	v_pk_mul_f32 v[128:129], v[76:77], v[76:77]
	v_add_f32_e32 v126, v126, v127
	v_add_f32_e32 v126, v128, v126
	v_pk_mul_f32 v[130:131], v[118:119], v[118:119]
	v_add_f32_e32 v126, v129, v126
	v_pk_add_f32 v[78:79], v[82:83], v[114:115]
	v_add_f32_e32 v126, v130, v126
	v_pk_mul_f32 v[132:133], v[78:79], v[78:79]
	s_waitcnt vmcnt(11)
	v_lshlrev_b32_e32 v80, 16, v142
	v_and_b32_e32 v81, 0xffff0000, v142
	v_add_f32_e32 v126, v131, v126
	v_pk_add_f32 v[114:115], v[84:85], v[80:81]
	v_add_f32_e32 v126, v132, v126
	v_pk_mul_f32 v[84:85], v[114:115], v[114:115]
	v_lshlrev_b32_e32 v80, 16, v143
	v_and_b32_e32 v81, 0xffff0000, v143
	v_add_f32_e32 v126, v133, v126
	v_pk_add_f32 v[110:111], v[86:87], v[80:81]
	v_add_f32_e32 v84, v84, v126
	v_pk_mul_f32 v[86:87], v[110:111], v[110:111]
	s_waitcnt vmcnt(10)
	v_lshlrev_b32_e32 v80, 16, v144
	v_and_b32_e32 v81, 0xffff0000, v144
	v_add_f32_e32 v84, v85, v84
	v_pk_add_f32 v[82:83], v[88:89], v[80:81]
	v_add_f32_e32 v84, v86, v84
	v_pk_mul_f32 v[88:89], v[82:83], v[82:83]
	v_lshlrev_b32_e32 v80, 16, v145
	v_and_b32_e32 v81, 0xffff0000, v145
	v_add_f32_e32 v84, v87, v84
	v_and_b32_e32 v86, 64, v239
	v_pk_add_f32 v[80:81], v[90:91], v[80:81]
	v_add_f32_e32 v84, v88, v84
	v_xor_b32_e32 v85, 32, v239
	v_add_u32_e32 v86, 64, v86
	v_pk_mul_f32 v[90:91], v[80:81], v[80:81]
	v_add_f32_e32 v84, v89, v84
	v_cmp_lt_i32_e32 vcc, v85, v86
	v_add_f32_e32 v84, v90, v84
	v_add_f32_e32 v84, v91, v84
	v_cndmask_b32_e32 v85, v239, v85, vcc
	v_lshlrev_b32_e32 v85, 2, v85
	ds_bpermute_b32 v85, v85, v84
	v_cmp_eq_u32_e32 vcc, 0, v52
	s_and_saveexec_b64 s[12:13], vcc
	s_cbranch_execz .Lg3b_519
	s_waitcnt lgkmcnt(0)
	v_add_f32_e32 v84, v84, v85
	v_lshl_add_u32 v85, v75, 2, s15
	v_add_u32_e32 v85, 0x1cd00, v85
	ds_write_b32 v85, v84
; __device__ __forceinline__ unsigned cvt2(float lo, float hi) { const cvf2_t v = {lo, hi}; return __builtin_bit_cast(unsigned, __builtin_convertvector(v, cvb2_t)); }
; __device__ __forceinline__ float fexp(float x) { return __builtin_amdgcn_exp2f(x * 1.4426950408889634f); }
; __device__ __forceinline__ void g3_unit(LAS float* part, int c, int h, const bf16* ACT, const bf16* OI, const bf16* QT, const bf16* SCT, const float* gnorm  , bf16* MIX) {
;     ...
;     __syncthreads();
;     const float tot = part[tb * 32 + r] + part[(tb + 2) * 32 + r] + part[(tb + 4) * 32 + r] + part[(tb + 6) * 32 + r];
;     const float rstd = __builtin_amdgcn_rsqf(tot * (1.f / 128.f) + RMS_EPS);
;     bf16* mp = MIX + (size_t)row * 1024 + h * 128 + jb * 32 + 8 * hh;
;     v2u yq[4];
; #pragma unroll
;     for (int q = 0; q < 4; ++q) { const v2u gg = ggv[q]; const f32x4 gn = gnv[q];
;       float gv[4] = {bf2f((unsigned short)(gg.x & 0xffffu)), bf2f((unsigned short)(gg.x >> 16)), bf2f((unsigned short)(gg.y & 0xffffu)), bf2f((unsigned short)(gg.y >> 16))}; float y[4];
; #pragma unroll
;       for (int e = 0; e < 4; ++e) { const float sg = gv[e] * __builtin_amdgcn_rcpf(1.f + fexp(-gv[e])); y[e] = acc[4 * q + e] * rstd * gn[e] * sg; }
;       yq[q] = (v2u){cvt2(y[0], y[1]), cvt2(y[2], y[3])}; }
; #pragma unroll
;     for (int q = 0; q < 4; q += 2) *(v4u*)(mp + 8 * q) = pair16(yq[q], yq[q + 1]);
.Lg3b_519:
	s_or_b64 exec, exec, s[12:13]
	s_lshl_b32 s12, s14, 2
	s_add_i32 s12, s12, 0
	v_lshl_add_u32 v75, v75, 2, s12
	v_add_u32_e32 v75, 0x1cd00, v75
	s_waitcnt lgkmcnt(0)
	s_barrier
	ds_read2st64_b32 v[12:13], v3 offset1:1
	s_waitcnt vmcnt(7)
	v_lshlrev_b32_e32 v16, 16, v48
	v_and_b32_e32 v17, 0xffff0000, v48
	v_lshlrev_b32_e32 v15, 3, v52
	s_lshl_b32 s72, s72, 1
	s_waitcnt lgkmcnt(0)
	v_add_f32_e32 v14, v12, v13
	ds_read2st64_b32 v[12:13], v3 offset0:2 offset1:3
	s_waitcnt lgkmcnt(0)
	v_add_f32_e32 v3, v14, v12
	v_add_f32_e32 v3, v3, v13
	v_fmamk_f32 v3, v3, 0x3c000000, v1
	v_rsq_f32_e32 v14, v3
	v_mul_f32_e32 v3, 0xbfb8aa3b, v16
	v_exp_f32_e32 v3, v3
	v_lshlrev_b64 v[12:13], 11, v[196:197]
	v_pk_mul_f32 v[4:5], v[4:5], v[14:15] op_sel_hi:[1,0]
	v_pk_mul_f32 v[6:7], v[6:7], v[14:15] op_sel_hi:[1,0]
	v_add_f32_e32 v3, 1.0, v3
	v_rcp_f32_e32 v18, v3
	v_mul_f32_e32 v3, 0xbfb8aa3b, v17
	v_exp_f32_e32 v3, v3
	s_waitcnt vmcnt(6)
	v_pk_mul_f32 v[4:5], v[34:35], v[4:5]
	s_waitcnt vmcnt(5)
	v_pk_mul_f32 v[6:7], v[30:31], v[6:7]
	v_pk_mul_f32 v[10:11], v[10:11], v[14:15] op_sel_hi:[1,0]
	v_add_f32_e32 v3, 1.0, v3
	v_rcp_f32_e32 v19, v3
	s_waitcnt vmcnt(0)
	v_pk_mul_f32 v[10:11], v[20:21], v[10:11]
	v_lshl_add_u64 v[12:13], s[10:11], 0, v[12:13]
	v_pk_mul_f32 v[8:9], v[8:9], v[14:15] op_sel_hi:[1,0]
	v_pk_mul_f32 v[16:17], v[18:19], v[16:17]
	v_pk_mul_f32 v[18:19], v[50:51], v[14:15] op_sel_hi:[1,0]
	v_lshl_add_u64 v[12:13], v[12:13], 0, s[72:73]
	v_pk_mul_f32 v[18:19], v[32:33], v[18:19]
	v_pk_mul_f32 v[8:9], v[22:23], v[8:9]
	v_pk_mul_f32 v[16:17], v[16:17], v[18:19]
	v_lshlrev_b32_e32 v18, 16, v49
	v_mul_f32_e32 v3, 0xbfb8aa3b, v18
	v_exp_f32_e32 v3, v3
	v_and_b32_e32 v19, 0xffff0000, v49
	v_lshl_add_u64 v[12:13], s[8:9], 1, v[12:13]
	v_lshlrev_b32_e32 v196, 1, v15
	v_add_f32_e32 v3, 1.0, v3
	v_rcp_f32_e32 v32, v3
	v_mul_f32_e32 v3, 0xbfb8aa3b, v19
	v_exp_f32_e32 v3, v3
	s_mov_b64 s[28:29], 0x13d00000
	v_add_f32_e32 v3, 1.0, v3
	v_rcp_f32_e32 v33, v3
	s_nop 0
	v_pk_mul_f32 v[18:19], v[32:33], v[18:19]
	s_nop 0
	v_pk_mul_f32 v[18:19], v[18:19], v[4:5]
	v_cvt_pk_bf16_f32 v4, v16, v17
	v_lshlrev_b32_e32 v16, 16, v44
	v_mul_f32_e32 v3, 0xbfb8aa3b, v16
	v_exp_f32_e32 v3, v3
	v_and_b32_e32 v17, 0xffff0000, v44
	v_cvt_pk_bf16_f32 v5, v18, v19
	v_add_f32_e32 v3, 1.0, v3
	v_rcp_f32_e32 v18, v3
	v_mul_f32_e32 v3, 0xbfb8aa3b, v17
	v_exp_f32_e32 v3, v3
	s_nop 0
	v_add_f32_e32 v3, 1.0, v3
	v_rcp_f32_e32 v19, v3
	s_nop 0
	v_pk_mul_f32 v[16:17], v[18:19], v[16:17]
	v_pk_mul_f32 v[18:19], v[46:47], v[14:15] op_sel_hi:[1,0]
	s_nop 0
	v_pk_mul_f32 v[18:19], v[28:29], v[18:19]
	s_nop 0
	v_pk_mul_f32 v[16:17], v[16:17], v[18:19]
	v_lshlrev_b32_e32 v18, 16, v45
	v_mul_f32_e32 v3, 0xbfb8aa3b, v18
	v_exp_f32_e32 v3, v3
	v_and_b32_e32 v19, 0xffff0000, v45
	v_add_f32_e32 v3, 1.0, v3
	v_rcp_f32_e32 v28, v3
	v_mul_f32_e32 v3, 0xbfb8aa3b, v19
	v_exp_f32_e32 v3, v3
	s_nop 0
	v_add_f32_e32 v3, 1.0, v3
	v_rcp_f32_e32 v29, v3
	s_nop 0
	v_pk_mul_f32 v[18:19], v[28:29], v[18:19]
	s_nop 0
	v_pk_mul_f32 v[18:19], v[18:19], v[6:7]
	v_cvt_pk_bf16_f32 v6, v16, v17
	v_lshlrev_b32_e32 v16, 16, v40
	v_mul_f32_e32 v3, 0xbfb8aa3b, v16
	v_exp_f32_e32 v3, v3
	v_and_b32_e32 v17, 0xffff0000, v40
	v_cvt_pk_bf16_f32 v7, v18, v19
	v_permlane32_swap_b32_e32 v4, v6
	v_add_f32_e32 v3, 1.0, v3
	v_rcp_f32_e32 v18, v3
	v_mul_f32_e32 v3, 0xbfb8aa3b, v17
	v_exp_f32_e32 v3, v3
	v_permlane32_swap_b32_e32 v5, v7
	v_add_f32_e32 v3, 1.0, v3
	v_rcp_f32_e32 v19, v3
	s_nop 0
	v_pk_mul_f32 v[16:17], v[18:19], v[16:17]
	v_pk_mul_f32 v[18:19], v[42:43], v[14:15] op_sel_hi:[1,0]
	s_nop 0
	v_pk_mul_f32 v[18:19], v[24:25], v[18:19]
	s_nop 0
	v_pk_mul_f32 v[16:17], v[16:17], v[18:19]
	v_lshlrev_b32_e32 v18, 16, v41
	v_mul_f32_e32 v3, 0xbfb8aa3b, v18
	v_exp_f32_e32 v3, v3
	v_and_b32_e32 v19, 0xffff0000, v41
	v_cvt_pk_bf16_f32 v16, v16, v17
	v_add_f32_e32 v3, 1.0, v3
	v_rcp_f32_e32 v24, v3
	v_mul_f32_e32 v3, 0xbfb8aa3b, v19
	v_exp_f32_e32 v3, v3
	s_nop 0
	v_add_f32_e32 v3, 1.0, v3
	v_rcp_f32_e32 v25, v3
	s_nop 0
	v_pk_mul_f32 v[18:19], v[24:25], v[18:19]
	v_pk_mul_f32 v[24:25], v[38:39], v[14:15] op_sel_hi:[1,0]
	s_nop 0
	v_pk_mul_f32 v[24:25], v[26:27], v[24:25]
	s_nop 0
	v_pk_mul_f32 v[18:19], v[18:19], v[24:25]
	s_nop 0
	v_cvt_pk_bf16_f32 v17, v18, v19
	v_lshlrev_b32_e32 v18, 16, v36
	v_mul_f32_e32 v3, 0xbfb8aa3b, v18
	v_exp_f32_e32 v3, v3
	v_and_b32_e32 v19, 0xffff0000, v36
	v_add_f32_e32 v3, 1.0, v3
	v_rcp_f32_e32 v24, v3
	v_mul_f32_e32 v3, 0xbfb8aa3b, v19
	v_exp_f32_e32 v3, v3
	s_nop 0
	v_add_f32_e32 v3, 1.0, v3
	v_rcp_f32_e32 v25, v3
	s_nop 0
	v_pk_mul_f32 v[18:19], v[24:25], v[18:19]
	s_nop 0
	v_pk_mul_f32 v[10:11], v[18:19], v[10:11]
	v_lshlrev_b32_e32 v18, 16, v37
	v_mul_f32_e32 v3, 0xbfb8aa3b, v18
	v_exp_f32_e32 v3, v3
	v_and_b32_e32 v19, 0xffff0000, v37
	v_add_f32_e32 v3, 1.0, v3
	v_rcp_f32_e32 v20, v3
	v_mul_f32_e32 v3, 0xbfb8aa3b, v19
	v_exp_f32_e32 v3, v3
	s_nop 0
	v_add_f32_e32 v3, 1.0, v3
	v_rcp_f32_e32 v21, v3
	s_nop 0
	v_pk_mul_f32 v[18:19], v[20:21], v[18:19]
	s_nop 0
	v_pk_mul_f32 v[8:9], v[18:19], v[8:9]
	v_cvt_pk_bf16_f32 v18, v10, v11
	v_cvt_pk_bf16_f32 v19, v8, v9
	v_lshl_add_u64 v[8:9], v[12:13], 0, v[196:197]
	v_lshl_add_u64 v[10:11], v[8:9], 0, s[28:29]
	s_mov_b32 s28, 0x13d00000
	v_add_co_u32_e32 v8, vcc, s28, v8
	v_permlane32_swap_b32_e32 v16, v18
	s_nop 0
	v_addc_co_u32_e32 v9, vcc, 0, v9, vcc
	v_permlane32_swap_b32_e32 v17, v19
	global_store_dwordx4 v[8:9], v[4:7], off
	global_store_dwordx4 v[10:11], v[16:19], off offset:32
	ds_read2st64_b32 v[84:85], v75 offset1:1
	s_waitcnt vmcnt(7)
; __device__ __forceinline__ unsigned cvt2(float lo, float hi) { const cvf2_t v = {lo, hi}; return __builtin_bit_cast(unsigned, __builtin_convertvector(v, cvb2_t)); }
; __device__ __forceinline__ float fexp(float x) { return __builtin_amdgcn_exp2f(x * 1.4426950408889634f); }
; __device__ __forceinline__ void g3_unit(LAS float* part, int c, int h, const bf16* ACT, const bf16* OI, const bf16* QT, const bf16* SCT, const float* gnorm  , bf16* MIX) {
;     ...
;     __syncthreads();
;     const float tot = part[tb * 32 + r] + part[(tb + 2) * 32 + r] + part[(tb + 4) * 32 + r] + part[(tb + 6) * 32 + r];
;     const float rstd = __builtin_amdgcn_rsqf(tot * (1.f / 128.f) + RMS_EPS);
;     bf16* mp = MIX + (size_t)row * 1024 + h * 128 + jb * 32 + 8 * hh;
;     v2u yq[4];
; #pragma unroll
;     for (int q = 0; q < 4; ++q) { const v2u gg = ggv[q]; const f32x4 gn = gnv[q];
;       float gv[4] = {bf2f((unsigned short)(gg.x & 0xffffu)), bf2f((unsigned short)(gg.x >> 16)), bf2f((unsigned short)(gg.y & 0xffffu)), bf2f((unsigned short)(gg.y >> 16))}; float y[4];
; #pragma unroll
;       for (int e = 0; e < 4; ++e) { const float sg = gv[e] * __builtin_amdgcn_rcpf(1.f + fexp(-gv[e])); y[e] = acc[4 * q + e] * rstd * gn[e] * sg; }
;       yq[q] = (v2u){cvt2(y[0], y[1]), cvt2(y[2], y[3])}; }
; #pragma unroll
;     for (int q = 0; q < 4; q += 2) *(v4u*)(mp + 8 * q) = pair16(yq[q], yq[q + 1]);
;     __syncthreads();
	v_lshlrev_b32_e32 v88, 16, v120
	v_and_b32_e32 v89, 0xffff0000, v120
	v_lshlrev_b32_e32 v87, 3, v52
	s_waitcnt lgkmcnt(0)
	v_add_f32_e32 v86, v84, v85
	ds_read2st64_b32 v[84:85], v75 offset0:2 offset1:3
	s_waitcnt lgkmcnt(0)
	v_add_f32_e32 v75, v86, v84
	v_add_f32_e32 v75, v75, v85
	v_fmamk_f32 v75, v75, 0x3c000000, v1
	v_rsq_f32_e32 v86, v75
	v_mul_f32_e32 v75, 0xbfb8aa3b, v88
	v_exp_f32_e32 v75, v75
	v_lshlrev_b64 v[84:85], 11, v[148:149]
	v_pk_mul_f32 v[76:77], v[76:77], v[86:87] op_sel_hi:[1,0]
	v_pk_mul_f32 v[78:79], v[78:79], v[86:87] op_sel_hi:[1,0]
	v_add_f32_e32 v75, 1.0, v75
	v_rcp_f32_e32 v90, v75
	v_mul_f32_e32 v75, 0xbfb8aa3b, v89
	v_exp_f32_e32 v75, v75
	s_waitcnt vmcnt(6)
	v_pk_mul_f32 v[76:77], v[106:107], v[76:77]
	s_waitcnt vmcnt(5)
	v_pk_mul_f32 v[78:79], v[102:103], v[78:79]
	v_pk_mul_f32 v[82:83], v[82:83], v[86:87] op_sel_hi:[1,0]
	v_add_f32_e32 v75, 1.0, v75
	v_rcp_f32_e32 v91, v75
	v_pk_mul_f32 v[82:83], v[92:93], v[82:83]
	v_lshl_add_u64 v[84:85], s[10:11], 0, v[84:85]
	v_pk_mul_f32 v[80:81], v[80:81], v[86:87] op_sel_hi:[1,0]
	v_pk_mul_f32 v[88:89], v[90:91], v[88:89]
	v_pk_mul_f32 v[90:91], v[122:123], v[86:87] op_sel_hi:[1,0]
	v_lshl_add_u64 v[84:85], v[84:85], 0, s[72:73]
	v_pk_mul_f32 v[90:91], v[104:105], v[90:91]
	v_pk_mul_f32 v[80:81], v[94:95], v[80:81]
	v_pk_mul_f32 v[88:89], v[88:89], v[90:91]
	v_lshlrev_b32_e32 v90, 16, v121
	v_mul_f32_e32 v75, 0xbfb8aa3b, v90
	v_exp_f32_e32 v75, v75
	v_and_b32_e32 v91, 0xffff0000, v121
	v_lshl_add_u64 v[84:85], s[8:9], 1, v[84:85]
	v_lshlrev_b32_e32 v148, 1, v87
	v_add_f32_e32 v75, 1.0, v75
	v_rcp_f32_e32 v104, v75
	v_mul_f32_e32 v75, 0xbfb8aa3b, v91
	v_exp_f32_e32 v75, v75
	s_mov_b64 s[8:9], 0x13d00000
	s_mov_b64 s[10:11], 0
	v_add_f32_e32 v75, 1.0, v75
	v_rcp_f32_e32 v105, v75
	s_nop 0
	v_pk_mul_f32 v[90:91], v[104:105], v[90:91]
	s_nop 0
	v_pk_mul_f32 v[90:91], v[90:91], v[76:77]
	v_cvt_pk_bf16_f32 v76, v88, v89
	v_lshlrev_b32_e32 v88, 16, v116
	v_mul_f32_e32 v75, 0xbfb8aa3b, v88
	v_exp_f32_e32 v75, v75
	v_and_b32_e32 v89, 0xffff0000, v116
	v_cvt_pk_bf16_f32 v77, v90, v91
	v_add_f32_e32 v75, 1.0, v75
	v_rcp_f32_e32 v90, v75
	v_mul_f32_e32 v75, 0xbfb8aa3b, v89
	v_exp_f32_e32 v75, v75
	s_nop 0
	v_add_f32_e32 v75, 1.0, v75
	v_rcp_f32_e32 v91, v75
	s_nop 0
	v_pk_mul_f32 v[88:89], v[90:91], v[88:89]
	v_pk_mul_f32 v[90:91], v[118:119], v[86:87] op_sel_hi:[1,0]
	s_nop 0
	v_pk_mul_f32 v[90:91], v[100:101], v[90:91]
	s_nop 0
	v_pk_mul_f32 v[88:89], v[88:89], v[90:91]
	v_lshlrev_b32_e32 v90, 16, v117
	v_mul_f32_e32 v75, 0xbfb8aa3b, v90
	v_exp_f32_e32 v75, v75
	v_and_b32_e32 v91, 0xffff0000, v117
	v_add_f32_e32 v75, 1.0, v75
	v_rcp_f32_e32 v100, v75
	v_mul_f32_e32 v75, 0xbfb8aa3b, v91
	v_exp_f32_e32 v75, v75
	s_nop 0
	v_add_f32_e32 v75, 1.0, v75
	v_rcp_f32_e32 v101, v75
	s_nop 0
	v_pk_mul_f32 v[90:91], v[100:101], v[90:91]
	s_nop 0
	v_pk_mul_f32 v[90:91], v[90:91], v[78:79]
	v_cvt_pk_bf16_f32 v78, v88, v89
	v_lshlrev_b32_e32 v88, 16, v112
	v_mul_f32_e32 v75, 0xbfb8aa3b, v88
	v_exp_f32_e32 v75, v75
	v_and_b32_e32 v89, 0xffff0000, v112
	v_cvt_pk_bf16_f32 v79, v90, v91
	v_permlane32_swap_b32_e32 v76, v78
	v_add_f32_e32 v75, 1.0, v75
	v_rcp_f32_e32 v90, v75
	v_mul_f32_e32 v75, 0xbfb8aa3b, v89
	v_exp_f32_e32 v75, v75
	v_permlane32_swap_b32_e32 v77, v79
	v_add_f32_e32 v75, 1.0, v75
	v_rcp_f32_e32 v91, v75
	s_nop 0
	v_pk_mul_f32 v[88:89], v[90:91], v[88:89]
	v_pk_mul_f32 v[90:91], v[114:115], v[86:87] op_sel_hi:[1,0]
	s_nop 0
	v_pk_mul_f32 v[90:91], v[96:97], v[90:91]
	s_nop 0
	v_pk_mul_f32 v[88:89], v[88:89], v[90:91]
	v_lshlrev_b32_e32 v90, 16, v113
	v_mul_f32_e32 v75, 0xbfb8aa3b, v90
	v_exp_f32_e32 v75, v75
	v_and_b32_e32 v91, 0xffff0000, v113
	v_cvt_pk_bf16_f32 v88, v88, v89
	v_add_f32_e32 v75, 1.0, v75
	v_rcp_f32_e32 v96, v75
	v_mul_f32_e32 v75, 0xbfb8aa3b, v91
	v_exp_f32_e32 v75, v75
	s_nop 0
	v_add_f32_e32 v75, 1.0, v75
	v_rcp_f32_e32 v97, v75
	s_nop 0
	v_pk_mul_f32 v[90:91], v[96:97], v[90:91]
	v_pk_mul_f32 v[96:97], v[110:111], v[86:87] op_sel_hi:[1,0]
	s_nop 0
	v_pk_mul_f32 v[96:97], v[98:99], v[96:97]
	s_nop 0
	v_pk_mul_f32 v[90:91], v[90:91], v[96:97]
	s_nop 0
	v_cvt_pk_bf16_f32 v89, v90, v91
	v_lshlrev_b32_e32 v90, 16, v108
	v_mul_f32_e32 v75, 0xbfb8aa3b, v90
	v_exp_f32_e32 v75, v75
	v_and_b32_e32 v91, 0xffff0000, v108
	v_add_f32_e32 v75, 1.0, v75
	v_rcp_f32_e32 v96, v75
	v_mul_f32_e32 v75, 0xbfb8aa3b, v91
	v_exp_f32_e32 v75, v75
	s_nop 0
	v_add_f32_e32 v75, 1.0, v75
	v_rcp_f32_e32 v97, v75
	s_nop 0
	v_pk_mul_f32 v[90:91], v[96:97], v[90:91]
	s_nop 0
	v_pk_mul_f32 v[82:83], v[90:91], v[82:83]
	v_lshlrev_b32_e32 v90, 16, v109
	v_mul_f32_e32 v75, 0xbfb8aa3b, v90
	v_exp_f32_e32 v75, v75
	v_and_b32_e32 v91, 0xffff0000, v109
	v_add_f32_e32 v75, 1.0, v75
	v_rcp_f32_e32 v92, v75
	v_mul_f32_e32 v75, 0xbfb8aa3b, v91
	v_exp_f32_e32 v75, v75
	s_nop 0
	v_add_f32_e32 v75, 1.0, v75
	v_rcp_f32_e32 v93, v75
	s_nop 0
	v_pk_mul_f32 v[90:91], v[92:93], v[90:91]
	s_nop 0
	v_pk_mul_f32 v[80:81], v[90:91], v[80:81]
	v_cvt_pk_bf16_f32 v90, v82, v83
	v_cvt_pk_bf16_f32 v91, v80, v81
	v_lshl_add_u64 v[80:81], v[84:85], 0, v[148:149]
	v_lshl_add_u64 v[82:83], v[80:81], 0, s[8:9]
	s_mov_b32 s8, 0x13d00000
	v_add_co_u32_e32 v80, vcc, s8, v80
	v_permlane32_swap_b32_e32 v88, v90
	s_nop 0
	v_addc_co_u32_e32 v81, vcc, 0, v81, vcc
	v_permlane32_swap_b32_e32 v89, v91
	global_store_dwordx4 v[80:81], v[76:79], off offset:256
	global_store_dwordx4 v[82:83], v[88:91], off offset:288
	s_barrier
